# phase 5: workgroups without a sample-row unit delay their final y stores by 2 x s_sleep 127
# speedup vs baseline: 1.0424x; 1.0026x over previous
.LBB0_1306:
	s_or_b64 exec, exec, s[0:1]
	s_cmp_lt_u32 s92, 64
	s_cbranch_scc1 .Lp5d_skip
	s_sleep 127
	s_sleep 127
.Lp5d_skip:
	v_readlane_b32 s0, v251, 5
	v_readlane_b32 s12, v251, 17
	v_readlane_b32 s13, v251, 18
	v_readlane_b32 s14, v251, 19
	v_readlane_b32 s15, v251, 20
	v_lshl_add_u64 v[2:3], s[12:13], 0, v[66:67]
	v_lshl_add_u64 v[38:39], v[136:137], 2, s[82:83]
	v_lshl_add_u64 v[6:7], s[14:15], 0, v[66:67]
	s_barrier
	global_load_dwordx4 v[26:29], v[2:3], off
	global_load_dwordx4 v[18:21], v[2:3], off offset:64
	global_load_dwordx4 v[30:33], v[6:7], off
	global_load_dwordx4 v[22:25], v[6:7], off offset:64
	global_load_dwordx4 v[10:13], v[2:3], off offset:512
	s_nop 0
	global_load_dwordx4 v[2:5], v[2:3], off offset:576
	s_nop 0
	global_load_dwordx4 v[14:17], v[6:7], off offset:512
	s_nop 0
	global_load_dwordx4 v[6:9], v[6:7], off offset:576
	s_nop 0
	global_load_dword v41, v[144:145], off sc1
	global_load_dword v40, v[144:145], off offset:4 sc1
	global_load_dword v141, v[38:39], off sc1
	global_load_dword v140, v[38:39], off offset:4 sc1
	v_lshl_add_u64 v[38:39], v[146:147], 2, s[82:83]
	global_load_dword v147, v[38:39], off sc1
	global_load_dword v146, v[38:39], off offset:4 sc1
	v_lshl_add_u64 v[38:39], v[156:157], 2, s[82:83]
	global_load_dword v157, v[38:39], off sc1
	global_load_dword v156, v[38:39], off offset:4 sc1
	v_lshl_add_u64 v[38:39], v[158:159], 2, s[82:83]
	global_load_dword v195, v[38:39], off sc1
	global_load_dword v194, v[38:39], off offset:4 sc1
	v_or_b32_e32 v144, 16, v152
	v_lshlrev_b32_e32 v38, 1, v144
	v_ashrrev_i32_e32 v39, 31, v38
	v_lshl_add_u64 v[38:39], v[38:39], 2, s[82:83]
	global_load_dword v197, v[38:39], off sc1
	global_load_dword v196, v[38:39], off offset:4 sc1
	v_or_b32_e32 v136, 32, v152
	v_or_b32_e32 v38, 48, v152
	v_lshlrev_b32_e32 v158, 1, v136
	v_lshlrev_b32_e32 v192, 1, v38
	v_ashrrev_i32_e32 v159, 31, v158
	v_ashrrev_i32_e32 v193, 31, v192
	v_lshl_add_u64 v[158:159], v[158:159], 2, s[82:83]
	v_lshl_add_u64 v[192:193], v[192:193], 2, s[82:83]
	global_load_dword v199, v[158:159], off sc1
	global_load_dword v198, v[158:159], off offset:4 sc1
	global_load_dword v201, v[192:193], off sc1
	global_load_dword v200, v[192:193], off offset:4 sc1
	v_readlane_b32 s2, v251, 7
	v_readlane_b32 s3, v251, 8
	s_mov_b32 s2, 0x3a800000
	s_mov_b32 s3, 0x800000
	v_readlane_b32 s8, v251, 13
	v_readlane_b32 s9, v251, 14
	s_mov_b32 s8, 0x3727c5ac
	v_readlane_b32 s1, v251, 6
	v_readlane_b32 s4, v251, 9
	v_readlane_b32 s5, v251, 10
	v_readlane_b32 s6, v251, 11
	v_readlane_b32 s7, v251, 12
	v_lshlrev_b64 v[68:69], 12, v[68:69]
	v_lshl_add_u64 v[68:69], s[84:85], 0, v[68:69]
	v_lshl_add_u64 v[68:69], v[68:69], 0, v[66:67]
	v_lshlrev_b64 v[134:135], 12, v[134:135]
	v_lshl_add_u64 v[134:135], s[84:85], 0, v[134:135]
	v_lshl_add_u64 v[134:135], v[134:135], 0, v[66:67]
	v_readlane_b32 s10, v251, 15
	v_readlane_b32 s11, v251, 16
	s_waitcnt vmcnt(14)
	v_pk_mul_f32 v[206:207], v[40:41], s[2:3] op_sel_hi:[1,0]
	s_waitcnt vmcnt(12)
	v_pk_mul_f32 v[208:209], v[140:141], s[2:3] op_sel_hi:[1,0]
	v_mov_b32_e32 v41, v207
	v_mov_b32_e32 v40, v209
	v_mov_b32_e32 v140, v208
	v_mov_b32_e32 v141, v206
	v_pk_fma_f32 v[40:41], v[40:41], v[40:41], v[140:141] neg_lo:[1,0,0] neg_hi:[1,0,0]
	s_waitcnt vmcnt(10)
	v_pk_mul_f32 v[192:193], v[146:147], s[2:3] op_sel_hi:[1,0]
	s_waitcnt vmcnt(8)
	v_pk_mul_f32 v[158:159], v[156:157], s[2:3] op_sel_hi:[1,0]
	v_pk_add_f32 v[40:41], v[40:41], s[8:9] op_sel_hi:[1,0]
	s_waitcnt vmcnt(6)
	v_pk_mul_f32 v[156:157], v[194:195], s[2:3] op_sel_hi:[1,0]
	v_mov_b32_e32 v146, v159
	v_mov_b32_e32 v147, v193
	v_mov_b32_e32 v194, v158
	v_mov_b32_e32 v195, v192
	v_mul_f32_e32 v137, 0x4b800000, v40
	v_cmp_gt_f32_e64 s[0:1], s3, v40
	v_pk_fma_f32 v[140:141], v[146:147], v[146:147], v[194:195] neg_lo:[1,0,0] neg_hi:[1,0,0]
	v_mul_f32_e32 v39, 0x4b800000, v41
	v_cndmask_b32_e64 v40, v40, v137, s[0:1]
	v_pk_add_f32 v[140:141], v[140:141], s[8:9] op_sel_hi:[1,0]
	v_rsq_f32_e32 v40, v40
	v_mul_f32_e32 v145, 0x4b800000, v141
	v_cmp_gt_f32_e32 vcc, s3, v41
	v_cmp_gt_f32_e64 s[4:5], s3, v141
	s_waitcnt vmcnt(4)
	v_pk_mul_f32 v[146:147], v[196:197], s[2:3] op_sel_hi:[1,0]
	v_cndmask_b32_e32 v39, v41, v39, vcc
	v_cndmask_b32_e64 v41, v141, v145, s[4:5]
	v_rsq_f32_e32 v39, v39
	v_rsq_f32_e32 v41, v41
	v_mul_f32_e32 v141, 0x45800000, v40
	v_cndmask_b32_e64 v196, v40, v141, s[0:1]
	v_sub_f32_e32 v117, v117, v209
	v_sub_f32_e32 v116, v116, v209
	v_sub_f32_e32 v115, v115, v209
	v_sub_f32_e32 v114, v114, v209
	v_sub_f32_e32 v113, v113, v209
	v_sub_f32_e32 v112, v112, v209
	v_sub_f32_e32 v111, v111, v209
	v_sub_f32_e32 v110, v110, v209
	v_sub_f32_e32 v109, v109, v209
	v_sub_f32_e32 v108, v108, v209
	v_sub_f32_e32 v107, v107, v209
	v_sub_f32_e32 v106, v106, v209
	v_sub_f32_e32 v105, v105, v209
	v_sub_f32_e32 v104, v104, v209
	v_sub_f32_e32 v103, v103, v209
	v_sub_f32_e32 v102, v102, v209
	v_mov_b32_e32 v213, v156
	v_mul_f32_e32 v156, 0x4b800000, v140
	v_cmp_gt_f32_e64 s[6:7], s3, v140
	v_pk_mul_f32 v[114:115], v[114:115], v[196:197] op_sel_hi:[1,0]
	v_pk_mul_f32 v[116:117], v[116:117], v[196:197] op_sel_hi:[1,0]
	v_pk_mul_f32 v[110:111], v[110:111], v[196:197] op_sel_hi:[1,0]
	v_pk_mul_f32 v[112:113], v[112:113], v[196:197] op_sel_hi:[1,0]
	v_pk_mul_f32 v[106:107], v[106:107], v[196:197] op_sel_hi:[1,0]
	v_pk_mul_f32 v[108:109], v[108:109], v[196:197] op_sel_hi:[1,0]
	v_pk_mul_f32 v[102:103], v[102:103], v[196:197] op_sel_hi:[1,0]
	v_pk_mul_f32 v[104:105], v[104:105], v[196:197] op_sel_hi:[1,0]
	v_cndmask_b32_e64 v137, v140, v156, s[6:7]
	v_mul_f32_e32 v140, 0x45800000, v39
	v_mul_f32_e32 v145, 0x45800000, v41
	v_pk_fma_f32 v[116:117], v[28:29], v[116:117], v[32:33]
	v_pk_fma_f32 v[114:115], v[26:27], v[114:115], v[30:31]
	v_pk_fma_f32 v[112:113], v[20:21], v[112:113], v[24:25]
	v_pk_fma_f32 v[110:111], v[18:19], v[110:111], v[22:23]
	v_pk_fma_f32 v[108:109], v[12:13], v[108:109], v[16:17]
	v_pk_fma_f32 v[106:107], v[10:11], v[106:107], v[14:15]
	v_pk_fma_f32 v[104:105], v[4:5], v[104:105], v[8:9]
	v_pk_fma_f32 v[102:103], v[2:3], v[102:103], v[6:7]
	v_rsq_f32_e32 v137, v137
	v_cndmask_b32_e32 v194, v39, v140, vcc
	v_cndmask_b32_e64 v192, v41, v145, s[4:5]
	v_sub_f32_e32 v133, v133, v207
	v_sub_f32_e32 v132, v132, v207
	v_sub_f32_e32 v131, v131, v207
	v_sub_f32_e32 v130, v130, v207
	v_sub_f32_e32 v129, v129, v207
	v_sub_f32_e32 v128, v128, v207
	v_sub_f32_e32 v127, v127, v207
	v_sub_f32_e32 v126, v126, v207
	v_sub_f32_e32 v125, v125, v207
	v_sub_f32_e32 v124, v124, v207
	v_sub_f32_e32 v123, v123, v207
	v_sub_f32_e32 v122, v122, v207
	v_sub_f32_e32 v121, v121, v207
	v_sub_f32_e32 v120, v120, v207
	v_sub_f32_e32 v119, v119, v207
	v_sub_f32_e32 v118, v118, v207
	global_store_dwordx4 v[68:69], v[114:117], off nt
	global_store_dwordx4 v[68:69], v[110:113], off offset:64 nt
	global_store_dwordx4 v[68:69], v[106:109], off offset:512 nt
	global_store_dwordx4 v[68:69], v[102:105], off offset:576 nt
	v_lshlrev_b64 v[68:69], 12, v[138:139]
	v_sub_f32_e32 v101, v101, v193
	v_sub_f32_e32 v100, v100, v193
	v_sub_f32_e32 v99, v99, v193
	v_sub_f32_e32 v98, v98, v193
	v_sub_f32_e32 v97, v97, v193
	v_sub_f32_e32 v96, v96, v193
	v_sub_f32_e32 v95, v95, v193
	v_sub_f32_e32 v94, v94, v193
	v_sub_f32_e32 v93, v93, v193
	v_sub_f32_e32 v92, v92, v193
	v_sub_f32_e32 v91, v91, v193
	v_sub_f32_e32 v90, v90, v193
	v_sub_f32_e32 v89, v89, v193
	v_sub_f32_e32 v88, v88, v193
	v_sub_f32_e32 v87, v87, v193
	v_sub_f32_e32 v86, v86, v193
	v_pk_mul_f32 v[130:131], v[130:131], v[194:195] op_sel_hi:[1,0]
	v_pk_mul_f32 v[132:133], v[132:133], v[194:195] op_sel_hi:[1,0]
	v_pk_mul_f32 v[126:127], v[126:127], v[194:195] op_sel_hi:[1,0]
	v_pk_mul_f32 v[128:129], v[128:129], v[194:195] op_sel_hi:[1,0]
	v_pk_mul_f32 v[122:123], v[122:123], v[194:195] op_sel_hi:[1,0]
	v_pk_mul_f32 v[124:125], v[124:125], v[194:195] op_sel_hi:[1,0]
	v_pk_mul_f32 v[118:119], v[118:119], v[194:195] op_sel_hi:[1,0]
	v_pk_mul_f32 v[120:121], v[120:121], v[194:195] op_sel_hi:[1,0]
	v_pk_mul_f32 v[98:99], v[98:99], v[192:193] op_sel_hi:[1,0]
	v_pk_mul_f32 v[100:101], v[100:101], v[192:193] op_sel_hi:[1,0]
	v_lshl_add_u64 v[68:69], s[84:85], 0, v[68:69]
	v_pk_mul_f32 v[94:95], v[94:95], v[192:193] op_sel_hi:[1,0]
	v_pk_mul_f32 v[96:97], v[96:97], v[192:193] op_sel_hi:[1,0]
	v_pk_mul_f32 v[90:91], v[90:91], v[192:193] op_sel_hi:[1,0]
	v_pk_mul_f32 v[92:93], v[92:93], v[192:193] op_sel_hi:[1,0]
	v_pk_mul_f32 v[86:87], v[86:87], v[192:193] op_sel_hi:[1,0]
	v_pk_mul_f32 v[88:89], v[88:89], v[192:193] op_sel_hi:[1,0]
	v_mov_b32_e32 v211, v157
	v_mov_b32_e32 v210, v147
	v_mov_b32_e32 v212, v146
	v_pk_fma_f32 v[132:133], v[28:29], v[132:133], v[32:33]
	v_pk_fma_f32 v[130:131], v[26:27], v[130:131], v[30:31]
	v_pk_fma_f32 v[128:129], v[20:21], v[128:129], v[24:25]
	v_pk_fma_f32 v[126:127], v[18:19], v[126:127], v[22:23]
	v_pk_fma_f32 v[124:125], v[12:13], v[124:125], v[16:17]
	v_pk_fma_f32 v[122:123], v[10:11], v[122:123], v[14:15]
	v_pk_fma_f32 v[120:121], v[4:5], v[120:121], v[8:9]
	v_pk_fma_f32 v[118:119], v[2:3], v[118:119], v[6:7]
	v_pk_fma_f32 v[100:101], v[28:29], v[100:101], v[32:33]
	v_pk_fma_f32 v[98:99], v[26:27], v[98:99], v[30:31]
	v_lshl_add_u64 v[68:69], v[68:69], 0, v[66:67]
	v_pk_fma_f32 v[96:97], v[20:21], v[96:97], v[24:25]
	v_pk_fma_f32 v[94:95], v[18:19], v[94:95], v[22:23]
	v_pk_fma_f32 v[92:93], v[12:13], v[92:93], v[16:17]
	v_pk_fma_f32 v[90:91], v[10:11], v[90:91], v[14:15]
	v_pk_fma_f32 v[88:89], v[4:5], v[88:89], v[8:9]
	v_pk_fma_f32 v[86:87], v[2:3], v[86:87], v[6:7]
	v_pk_fma_f32 v[40:41], v[210:211], v[210:211], v[212:213] neg_lo:[1,0,0] neg_hi:[1,0,0]
	global_store_dwordx4 v[134:135], v[130:133], off nt
	global_store_dwordx4 v[134:135], v[126:129], off offset:64 nt
	global_store_dwordx4 v[134:135], v[122:125], off offset:512 nt
	global_store_dwordx4 v[134:135], v[118:121], off offset:576 nt
	global_store_dwordx4 v[68:69], v[98:101], off nt
	global_store_dwordx4 v[68:69], v[94:97], off offset:64 nt
	global_store_dwordx4 v[68:69], v[90:93], off offset:512 nt
	global_store_dwordx4 v[68:69], v[86:89], off offset:576 nt
	v_lshlrev_b64 v[68:69], 12, v[142:143]
	v_mul_f32_e32 v146, 0x45800000, v137
	v_pk_add_f32 v[40:41], v[40:41], s[8:9] op_sel_hi:[1,0]
	v_lshl_add_u64 v[68:69], s[84:85], 0, v[68:69]
	v_mul_f32_e32 v39, 0x4b800000, v41
	v_cmp_gt_f32_e32 vcc, s3, v41
	v_cndmask_b32_e64 v158, v137, v146, s[6:7]
	v_lshl_add_u64 v[86:87], v[68:69], 0, v[66:67]
	v_sub_f32_e32 v69, v81, v159
	v_sub_f32_e32 v68, v80, v159
	v_cndmask_b32_e32 v39, v41, v39, vcc
	v_pk_mul_f32 v[68:69], v[68:69], v[158:159] op_sel_hi:[1,0]
	v_rsq_f32_e32 v39, v39
	v_mul_f32_e32 v41, 0x4b800000, v40
	v_cmp_gt_f32_e64 s[0:1], s3, v40
	v_pk_fma_f32 v[80:81], v[20:21], v[68:69], v[24:25]
	v_sub_f32_e32 v69, v77, v159
	v_sub_f32_e32 v68, v76, v159
	v_cndmask_b32_e64 v40, v40, v41, s[0:1]
	v_pk_mul_f32 v[68:69], v[68:69], v[158:159] op_sel_hi:[1,0]
	v_rsq_f32_e32 v145, v40
	v_pk_fma_f32 v[76:77], v[12:13], v[68:69], v[16:17]
	v_sub_f32_e32 v69, v73, v159
	v_sub_f32_e32 v68, v72, v159
	v_sub_f32_e32 v71, v71, v159
	v_sub_f32_e32 v70, v70, v159
	v_pk_mul_f32 v[72:73], v[70:71], v[158:159] op_sel_hi:[1,0]
	v_pk_mul_f32 v[68:69], v[68:69], v[158:159] op_sel_hi:[1,0]
	v_mul_f32_e32 v40, 0x45800000, v39
	v_pk_fma_f32 v[70:71], v[4:5], v[68:69], v[8:9]
	v_pk_fma_f32 v[68:69], v[2:3], v[72:73], v[6:7]
	v_cndmask_b32_e32 v156, v39, v40, vcc
	v_sub_f32_e32 v75, v75, v159
	v_sub_f32_e32 v74, v74, v159
	global_store_dwordx4 v[86:87], v[68:71], off offset:576 nt
	v_sub_f32_e32 v57, v57, v157
	v_sub_f32_e32 v56, v56, v157
	v_lshlrev_b64 v[68:69], 12, v[152:153]
	v_sub_f32_e32 v55, v55, v157
	v_sub_f32_e32 v54, v54, v157
	v_sub_f32_e32 v53, v53, v157
	v_sub_f32_e32 v52, v52, v157
	v_sub_f32_e32 v51, v51, v157
	v_sub_f32_e32 v50, v50, v157
	v_mul_f32_e32 v39, 0x45800000, v145
	v_pk_mul_f32 v[74:75], v[74:75], v[158:159] op_sel_hi:[1,0]
	v_lshl_add_u64 v[68:69], s[84:85], 0, v[68:69]
	v_pk_mul_f32 v[54:55], v[54:55], v[156:157] op_sel_hi:[1,0]
	v_pk_mul_f32 v[56:57], v[56:57], v[156:157] op_sel_hi:[1,0]
	v_pk_mul_f32 v[50:51], v[50:51], v[156:157] op_sel_hi:[1,0]
	v_pk_mul_f32 v[52:53], v[52:53], v[156:157] op_sel_hi:[1,0]
	s_waitcnt vmcnt(15)
	v_pk_mul_f32 v[140:141], v[198:199], s[2:3] op_sel_hi:[1,0]
	s_waitcnt vmcnt(13)
	v_pk_mul_f32 v[40:41], v[200:201], s[2:3] op_sel_hi:[1,0]
	v_cndmask_b32_e64 v146, v145, v39, s[0:1]
	v_pk_fma_f32 v[74:75], v[10:11], v[74:75], v[14:15]
	v_lshl_add_u64 v[68:69], v[68:69], 0, v[66:67]
	v_pk_fma_f32 v[56:57], v[12:13], v[56:57], v[16:17]
	v_pk_fma_f32 v[54:55], v[10:11], v[54:55], v[14:15]
	v_pk_fma_f32 v[52:53], v[4:5], v[52:53], v[8:9]
	v_pk_fma_f32 v[50:51], v[2:3], v[50:51], v[6:7]
	v_ashrrev_i32_e32 v145, 31, v144
	v_mov_b32_e32 v198, v41
	v_mov_b32_e32 v199, v141
	v_mov_b32_e32 v200, v40
	v_mov_b32_e32 v201, v140
	v_sub_f32_e32 v85, v85, v159
	v_sub_f32_e32 v84, v84, v159
	v_sub_f32_e32 v83, v83, v159
	v_sub_f32_e32 v82, v82, v159
	global_store_dwordx4 v[86:87], v[74:77], off offset:512 nt
	v_sub_f32_e32 v65, v65, v157
	v_sub_f32_e32 v64, v64, v157
	v_sub_f32_e32 v63, v63, v157
	v_sub_f32_e32 v62, v62, v157
	global_store_dwordx4 v[68:69], v[54:57], off offset:512 nt
	global_store_dwordx4 v[68:69], v[50:53], off offset:576 nt
	v_pk_fma_f32 v[198:199], v[198:199], v[198:199], v[200:201] neg_lo:[1,0,0] neg_hi:[1,0,0]
	v_lshlrev_b64 v[54:55], 12, v[144:145]
	v_sub_f32_e32 v51, v173, v147
	v_sub_f32_e32 v50, v172, v147
	v_sub_f32_e32 v53, v171, v147
	v_sub_f32_e32 v52, v170, v147
	v_pk_mul_f32 v[82:83], v[82:83], v[158:159] op_sel_hi:[1,0]
	v_pk_mul_f32 v[84:85], v[84:85], v[158:159] op_sel_hi:[1,0]
	v_pk_mul_f32 v[62:63], v[62:63], v[156:157] op_sel_hi:[1,0]
	v_pk_mul_f32 v[64:65], v[64:65], v[156:157] op_sel_hi:[1,0]
	v_pk_mul_f32 v[56:57], v[52:53], v[146:147] op_sel_hi:[1,0]
	v_pk_mul_f32 v[50:51], v[50:51], v[146:147] op_sel_hi:[1,0]
	v_lshl_add_u64 v[54:55], s[84:85], 0, v[54:55]
	v_pk_add_f32 v[198:199], v[198:199], s[8:9] op_sel_hi:[1,0]
	v_pk_fma_f32 v[84:85], v[28:29], v[84:85], v[32:33]
	v_pk_fma_f32 v[82:83], v[26:27], v[82:83], v[30:31]
	v_pk_fma_f32 v[64:65], v[28:29], v[64:65], v[32:33]
	v_pk_fma_f32 v[62:63], v[26:27], v[62:63], v[30:31]
	v_pk_fma_f32 v[52:53], v[28:29], v[50:51], v[32:33]
	v_pk_fma_f32 v[50:51], v[26:27], v[56:57], v[30:31]
	v_lshl_add_u64 v[54:55], v[54:55], 0, v[66:67]
	v_mul_f32_e32 v40, 0x4b800000, v199
	v_cmp_gt_f32_e32 vcc, s3, v199
	global_store_dwordx4 v[86:87], v[82:85], off nt
	v_sub_f32_e32 v79, v79, v159
	v_sub_f32_e32 v78, v78, v159
	global_store_dwordx4 v[68:69], v[62:65], off nt
	v_sub_f32_e32 v61, v61, v157
	v_sub_f32_e32 v60, v60, v157
	v_sub_f32_e32 v59, v59, v157
	v_sub_f32_e32 v58, v58, v157
	global_store_dwordx4 v[54:55], v[50:53], off nt
	v_cndmask_b32_e32 v40, v199, v40, vcc
	v_mul_f32_e32 v137, 0x4b800000, v198
	v_sub_f32_e32 v51, v165, v147
	v_sub_f32_e32 v50, v164, v147
	v_sub_f32_e32 v53, v161, v147
	v_sub_f32_e32 v52, v160, v147
	v_cmp_gt_f32_e64 s[4:5], s3, v198
	v_pk_mul_f32 v[78:79], v[78:79], v[158:159] op_sel_hi:[1,0]
	v_pk_mul_f32 v[58:59], v[58:59], v[156:157] op_sel_hi:[1,0]
	v_pk_mul_f32 v[60:61], v[60:61], v[156:157] op_sel_hi:[1,0]
	v_pk_mul_f32 v[56:57], v[52:53], v[146:147] op_sel_hi:[1,0]
	v_pk_mul_f32 v[50:51], v[50:51], v[146:147] op_sel_hi:[1,0]
	v_rsq_f32_e32 v40, v40
	v_cndmask_b32_e64 v137, v198, v137, s[4:5]
	v_pk_fma_f32 v[78:79], v[18:19], v[78:79], v[22:23]
	v_pk_fma_f32 v[60:61], v[20:21], v[60:61], v[24:25]
	v_pk_fma_f32 v[58:59], v[18:19], v[58:59], v[22:23]
	v_pk_fma_f32 v[52:53], v[20:21], v[50:51], v[24:25]
	v_pk_fma_f32 v[50:51], v[18:19], v[56:57], v[22:23]
	v_rsq_f32_e32 v137, v137
	global_store_dwordx4 v[86:87], v[78:81], off offset:64 nt
	global_store_dwordx4 v[68:69], v[58:61], off offset:64 nt
	global_store_dwordx4 v[54:55], v[50:53], off offset:64 nt
	v_mul_f32_e32 v39, 0x45800000, v40
	v_cndmask_b32_e32 v140, v40, v39, vcc
	v_sub_f32_e32 v51, v169, v147
	v_sub_f32_e32 v50, v168, v147
	v_sub_f32_e32 v53, v167, v147
	v_sub_f32_e32 v52, v166, v147
	v_pk_mul_f32 v[56:57], v[52:53], v[146:147] op_sel_hi:[1,0]
	v_pk_mul_f32 v[50:51], v[50:51], v[146:147] op_sel_hi:[1,0]
	v_mul_f32_e32 v39, 0x45800000, v137
	v_pk_fma_f32 v[52:53], v[12:13], v[50:51], v[16:17]
	v_pk_fma_f32 v[50:51], v[10:11], v[56:57], v[14:15]
	global_store_dwordx4 v[54:55], v[50:53], off offset:512 nt
	v_cndmask_b32_e64 v40, v137, v39, s[4:5]
	v_ashrrev_i32_e32 v137, 31, v136
	v_sub_f32_e32 v51, v177, v147
	v_sub_f32_e32 v50, v176, v147
	v_sub_f32_e32 v53, v175, v147
	v_sub_f32_e32 v52, v174, v147
	v_pk_mul_f32 v[56:57], v[52:53], v[146:147] op_sel_hi:[1,0]
	v_pk_mul_f32 v[50:51], v[50:51], v[146:147] op_sel_hi:[1,0]
	v_ashrrev_i32_e32 v39, 31, v38
	v_pk_fma_f32 v[52:53], v[4:5], v[50:51], v[8:9]
	v_pk_fma_f32 v[50:51], v[2:3], v[56:57], v[6:7]
	global_store_dwordx4 v[54:55], v[50:53], off offset:576 nt
	v_lshlrev_b64 v[54:55], 12, v[136:137]
	v_lshl_add_u64 v[54:55], s[84:85], 0, v[54:55]
	v_sub_f32_e32 v51, v187, v141
	v_sub_f32_e32 v50, v186, v141
	v_sub_f32_e32 v53, v185, v141
	v_sub_f32_e32 v52, v184, v141
	v_pk_mul_f32 v[56:57], v[52:53], v[140:141] op_sel_hi:[1,0]
	v_pk_mul_f32 v[50:51], v[50:51], v[140:141] op_sel_hi:[1,0]
	v_lshl_add_u64 v[54:55], v[54:55], 0, v[66:67]
	v_pk_fma_f32 v[52:53], v[28:29], v[50:51], v[32:33]
	v_pk_fma_f32 v[50:51], v[26:27], v[56:57], v[30:31]
	global_store_dwordx4 v[54:55], v[50:53], off nt
	v_lshlrev_b64 v[38:39], 12, v[38:39]
	s_nop 0
	v_sub_f32_e32 v51, v179, v141
	v_sub_f32_e32 v50, v178, v141
	v_sub_f32_e32 v53, v155, v141
	v_sub_f32_e32 v52, v154, v141
	v_pk_mul_f32 v[56:57], v[52:53], v[140:141] op_sel_hi:[1,0]
	v_pk_mul_f32 v[50:51], v[50:51], v[140:141] op_sel_hi:[1,0]
	s_nop 0
	v_pk_fma_f32 v[52:53], v[20:21], v[50:51], v[24:25]
	v_pk_fma_f32 v[50:51], v[18:19], v[56:57], v[22:23]
	global_store_dwordx4 v[54:55], v[50:53], off offset:64 nt
	s_nop 1
	v_sub_f32_e32 v51, v183, v141
	v_sub_f32_e32 v50, v182, v141
	v_sub_f32_e32 v53, v181, v141
	v_sub_f32_e32 v52, v180, v141
	v_pk_mul_f32 v[56:57], v[52:53], v[140:141] op_sel_hi:[1,0]
	v_pk_mul_f32 v[50:51], v[50:51], v[140:141] op_sel_hi:[1,0]
	s_nop 0
	v_pk_fma_f32 v[52:53], v[12:13], v[50:51], v[16:17]
	v_pk_fma_f32 v[50:51], v[10:11], v[56:57], v[14:15]
	global_store_dwordx4 v[54:55], v[50:53], off offset:512 nt
	s_nop 1
	v_sub_f32_e32 v51, v191, v141
	v_sub_f32_e32 v50, v190, v141
	v_sub_f32_e32 v53, v189, v141
	v_sub_f32_e32 v52, v188, v141
	v_pk_mul_f32 v[56:57], v[52:53], v[140:141] op_sel_hi:[1,0]
	v_pk_mul_f32 v[50:51], v[50:51], v[140:141] op_sel_hi:[1,0]
	s_nop 0
	v_pk_fma_f32 v[52:53], v[4:5], v[50:51], v[8:9]
	v_pk_fma_f32 v[50:51], v[2:3], v[56:57], v[6:7]
	global_store_dwordx4 v[54:55], v[50:53], off offset:576 nt
	s_nop 1
	v_sub_f32_e32 v53, v149, v41
	v_sub_f32_e32 v52, v148, v41
	v_sub_f32_e32 v51, v151, v41
	v_sub_f32_e32 v50, v150, v41
	v_pk_mul_f32 v[52:53], v[52:53], v[40:41] op_sel_hi:[1,0]
	v_pk_mul_f32 v[50:51], v[50:51], v[40:41] op_sel_hi:[1,0]
	v_pk_fma_f32 v[26:27], v[26:27], v[52:53], v[30:31]
	v_lshl_add_u64 v[30:31], s[84:85], 0, v[38:39]
	v_pk_fma_f32 v[28:29], v[28:29], v[50:51], v[32:33]
	v_lshl_add_u64 v[30:31], v[30:31], 0, v[66:67]
	global_store_dwordx4 v[30:31], v[26:29], off nt
	s_nop 1
	v_sub_f32_e32 v27, v49, v41
	v_sub_f32_e32 v26, v48, v41
	v_sub_f32_e32 v29, v47, v41
	v_sub_f32_e32 v28, v46, v41
	v_pk_mul_f32 v[28:29], v[28:29], v[40:41] op_sel_hi:[1,0]
	v_pk_mul_f32 v[26:27], v[26:27], v[40:41] op_sel_hi:[1,0]
	v_pk_fma_f32 v[18:19], v[18:19], v[28:29], v[22:23]
	v_pk_fma_f32 v[20:21], v[20:21], v[26:27], v[24:25]
	global_store_dwordx4 v[30:31], v[18:21], off offset:64 nt
	s_nop 1
	v_sub_f32_e32 v19, v45, v41
	v_sub_f32_e32 v18, v44, v41
	v_sub_f32_e32 v21, v43, v41
	v_sub_f32_e32 v20, v42, v41
	v_pk_mul_f32 v[20:21], v[20:21], v[40:41] op_sel_hi:[1,0]
	v_pk_mul_f32 v[18:19], v[18:19], v[40:41] op_sel_hi:[1,0]
	v_pk_fma_f32 v[10:11], v[10:11], v[20:21], v[14:15]
	v_pk_fma_f32 v[12:13], v[12:13], v[18:19], v[16:17]
	global_store_dwordx4 v[30:31], v[10:13], off offset:512 nt
	s_nop 1
	v_sub_f32_e32 v11, v37, v41
	v_sub_f32_e32 v10, v36, v41
	v_sub_f32_e32 v13, v35, v41
	v_sub_f32_e32 v12, v34, v41
	v_pk_mul_f32 v[12:13], v[12:13], v[40:41] op_sel_hi:[1,0]
	v_pk_mul_f32 v[10:11], v[10:11], v[40:41] op_sel_hi:[1,0]
	v_pk_fma_f32 v[2:3], v[2:3], v[12:13], v[6:7]
	v_pk_fma_f32 v[4:5], v[4:5], v[10:11], v[8:9]
	global_store_dwordx4 v[30:31], v[2:5], off offset:576 nt
